# P5 residual epilogue (f32 x loads): 16-deep rolling prefetch window with counted vmcnt instead of load-wait-store ladder
# speedup vs baseline: 1.0127x; 1.0120x over previous
; __device__ __forceinline__ unsigned cvt_pk_bf16(float lo, float hi) { return ::cvtpk(lo, hi); }
;     __device__ __forceinline__ void operator()(const f32x4 (&acc)[2][2][4][2], const Unit& u, int wr, int wc, int fr, int fq, int) const {
;         const int row0 = u.pm * BM + wr * 64 + fr, col0 = u.pn * BM + wc * 32 + 4 * fq;
; #pragma unroll
;         for (int ai = 0; ai < 2; ++ai)
; #pragma unroll
;             for (int m = 0; m < 4; ++m) { const int row = row0 + ai * HALF + m * 16; const size_t off = (size_t)row * 2048 + col0; float s = 0.f;
; #pragma unroll
;                 for (int bj = 0; bj < 2; ++bj)
; #pragma unroll
;                     for (int n = 0; n < 2; ++n) { const size_t o2 = off + bj * HALF + n * 16; f32x4 bs;
;                         if (MODE == 0) bs = __builtin_nontemporal_load((const f32x4*)(base + o2));
;                         else { const u32x2 b2 = *(const u32x2*)(xb + o2); bs[0] = __builtin_bit_cast(float, b2.x << 16); bs[1] = __builtin_bit_cast(float, b2.x & 0xffff0000u); bs[2] = __builtin_bit_cast(float, b2.y << 16); bs[3] = __builtin_bit_cast(float, b2.y & 0xffff0000u); }
;                         const f32x4 o = bs + acc[ai][bj][m][n];
;                         if (MODE == 2) __builtin_nontemporal_store(o, (f32x4*)(out + o2));
;                         else { s += (o[0] * o[0] + o[1] * o[1]) + (o[2] * o[2] + o[3] * o[3]); u32x2 w; w.x = cvt_pk_bf16(o[0], o[1]); w.y = cvt_pk_bf16(o[2], o[3]); *(u32x2*)(xb + o2) = w; } }
;                 if (MODE != 2) { s += __shfl_xor(s, 16); s += __shfl_xor(s, 32); if (fq == 0) ssq[(size_t)row * 32 + u.pn * 4 + wc] = s; } }
.LBB0_588:
	v_xor_b32_e32 v145, 16, v175
	v_cmp_lt_i32_e32 vcc, v145, v177
	v_lshl_add_u32 v144, s22, 8, v146
	v_lshl_or_b32 v142, s0, 8, v148
	v_cndmask_b32_e32 v145, v175, v145, vcc
	v_lshlrev_b32_e32 v153, 2, v145
	v_xor_b32_e32 v145, 32, v175
	v_cmp_lt_i32_e32 vcc, v145, v177
	v_ashrrev_i32_e32 v143, 31, v142
	v_readlane_b32 s48, v237, 29
	v_cndmask_b32_e32 v145, v175, v145, vcc
	v_lshlrev_b32_e32 v152, 2, v145
	v_ashrrev_i32_e32 v145, 31, v144
	v_lshlrev_b64 v[154:155], 11, v[144:145]
	v_lshl_add_u64 v[158:159], v[154:155], 0, v[142:143]
	v_readlane_b32 s49, v237, 30
	s_lshl_b32 s22, s0, 2
	s_ashr_i32 s23, s22, 31
	v_lshl_add_u64 v[160:161], v[158:159], 2, s[48:49]
	s_nop 4
	v_subrev_u32_e32 v170, s48, v160
	s_nop 1
	global_load_dwordx4 v[162:165], v170, s[48:49] nt
	global_load_dwordx4 v[166:169], v170, s[48:49] offset:64 nt
	global_load_dwordx4 v[180:183], v170, s[48:49] offset:512 nt
	global_load_dwordx4 v[184:187], v170, s[48:49] offset:576 nt
	v_add_u32_e32 v171, 0x20000, v170
	global_load_dwordx4 v[188:191], v171, s[48:49] nt
	global_load_dwordx4 v[192:195], v171, s[48:49] offset:64 nt
	global_load_dwordx4 v[196:199], v171, s[48:49] offset:512 nt
	global_load_dwordx4 v[200:203], v171, s[48:49] offset:576 nt
	v_add_u32_e32 v171, 0x40000, v170
	global_load_dwordx4 v[204:207], v171, s[48:49] nt
	global_load_dwordx4 v[208:211], v171, s[48:49] offset:64 nt
	global_load_dwordx4 v[212:215], v171, s[48:49] offset:512 nt
	global_load_dwordx4 v[216:219], v171, s[48:49] offset:576 nt
	v_add_u32_e32 v171, 0x60000, v170
	global_load_dwordx4 v[220:223], v171, s[48:49] nt
	global_load_dwordx4 v[224:227], v171, s[48:49] offset:64 nt
	global_load_dwordx4 v[228:231], v171, s[48:49] offset:512 nt
	global_load_dwordx4 v[232:235], v171, s[48:49] offset:576 nt
	s_waitcnt vmcnt(15)
	s_nop 1
	v_mov_b32_e32 v154, v162
	v_mov_b32_e32 v155, v163
	v_mov_b32_e32 v156, v164
	v_mov_b32_e32 v157, v165
	v_add_u32_e32 v171, 0x100000, v170
	global_load_dwordx4 v[162:165], v171, s[48:49] nt
	v_readlane_b32 s50, v237, 31
	v_readlane_b32 s51, v237, 32
	v_readlane_b32 s52, v237, 33
	v_readlane_b32 s53, v237, 34
	v_readlane_b32 s54, v237, 35
	v_readlane_b32 s55, v237, 36
	v_readlane_b32 s56, v237, 37
	v_readlane_b32 s57, v237, 38
	v_readlane_b32 s58, v237, 39
	v_readlane_b32 s59, v237, 40
	v_readlane_b32 s60, v237, 41
	v_readlane_b32 s61, v237, 42
	v_readlane_b32 s62, v237, 43
	v_readlane_b32 s63, v237, 44
	v_pk_add_f32 v[126:127], v[126:127], v[156:157]
	v_pk_add_f32 v[124:125], v[124:125], v[154:155]
	v_mul_f32_e32 v155, v127, v127
	v_mul_f32_e32 v154, v125, v125
	v_fmac_f32_e32 v154, v124, v124
	v_fmac_f32_e32 v155, v126, v126
	v_add_f32_e32 v156, v154, v155
	v_lshlrev_b64 v[154:155], 1, v[158:159]
	v_cvt_pk_bf16_f32 v124, v124, v125
	v_cvt_pk_bf16_f32 v125, v126, v127
	v_lshl_add_u64 v[126:127], s[80:81], 0, v[154:155]
	global_store_dwordx2 v[126:127], v[124:125], off
	s_waitcnt vmcnt(16)
	s_nop 1
	v_mov_b32_e32 v124, v166
	v_mov_b32_e32 v125, v167
	v_mov_b32_e32 v126, v168
	v_mov_b32_e32 v127, v169
	global_load_dwordx4 v[166:169], v171, s[48:49] offset:64 nt
	v_pk_add_f32 v[122:123], v[122:123], v[126:127]
	v_pk_add_f32 v[120:121], v[120:121], v[124:125]
	v_mul_f32_e32 v125, v123, v123
	v_mul_f32_e32 v124, v121, v121
	v_fmac_f32_e32 v124, v120, v120
	v_fmac_f32_e32 v125, v122, v122
	v_cvt_pk_bf16_f32 v120, v120, v121
	v_cvt_pk_bf16_f32 v121, v122, v123
	v_or_b32_e32 v122, 32, v154
	v_mov_b32_e32 v123, v155
	v_lshl_add_u64 v[122:123], s[80:81], 0, v[122:123]
	global_store_dwordx2 v[122:123], v[120:121], off
	s_waitcnt vmcnt(17)
	s_nop 1
	v_mov_b32_e32 v120, v180
	v_mov_b32_e32 v121, v181
	v_mov_b32_e32 v122, v182
	v_mov_b32_e32 v123, v183
	global_load_dwordx4 v[180:183], v171, s[48:49] offset:512 nt
	v_add_f32_e32 v124, v124, v125
	v_add_f32_e32 v124, v156, v124
	v_pk_add_f32 v[118:119], v[118:119], v[122:123]
	v_pk_add_f32 v[116:117], v[116:117], v[120:121]
	v_mul_f32_e32 v121, v119, v119
	v_mul_f32_e32 v120, v117, v117
	v_fmac_f32_e32 v120, v116, v116
	v_fmac_f32_e32 v121, v118, v118
	v_cvt_pk_bf16_f32 v116, v116, v117
	v_cvt_pk_bf16_f32 v117, v118, v119
	v_or_b32_e32 v118, 0x100, v154
	v_mov_b32_e32 v119, v155
	v_lshl_add_u64 v[118:119], s[80:81], 0, v[118:119]
	global_store_dwordx2 v[118:119], v[116:117], off
	s_waitcnt vmcnt(18)
	s_nop 1
	v_mov_b32_e32 v116, v184
	v_mov_b32_e32 v117, v185
	v_mov_b32_e32 v118, v186
	v_mov_b32_e32 v119, v187
	global_load_dwordx4 v[184:187], v171, s[48:49] offset:576 nt
	v_add_f32_e32 v120, v120, v121
	v_add_f32_e32 v120, v124, v120
	v_or_b32_e32 v154, 0x120, v154
	v_pk_add_f32 v[114:115], v[114:115], v[118:119]
	v_pk_add_f32 v[112:113], v[112:113], v[116:117]
	v_mul_f32_e32 v117, v115, v115
	v_mul_f32_e32 v116, v113, v113
	v_fmac_f32_e32 v116, v112, v112
	v_fmac_f32_e32 v117, v114, v114
	v_add_f32_e32 v116, v116, v117
	v_add_f32_e32 v116, v120, v116
	v_cvt_pk_bf16_f32 v112, v112, v113
	v_cvt_pk_bf16_f32 v113, v114, v115
	v_lshl_add_u64 v[114:115], s[80:81], 0, v[154:155]
	global_store_dwordx2 v[114:115], v[112:113], off
	ds_bpermute_b32 v112, v153, v116
	s_waitcnt lgkmcnt(0)
	v_add_f32_e32 v112, v116, v112
	ds_bpermute_b32 v113, v152, v112
	s_and_saveexec_b64 s[24:25], s[8:9]
	s_cbranch_execz .LBB0_590
	v_readlane_b32 s26, v237, 48
	v_lshlrev_b64 v[114:115], 7, v[144:145]
	v_readlane_b32 s27, v237, 49
	s_lshl_b32 s0, s40, 2
	s_waitcnt lgkmcnt(0)
	v_add_f32_e32 v112, v112, v113
	v_lshl_add_u64 v[114:115], s[26:27], 0, v[114:115]
	v_lshl_add_u64 v[114:115], s[22:23], 2, v[114:115]
	v_lshl_add_u64 v[114:115], v[114:115], 0, s[0:1]
	global_store_dword v[114:115], v112, off
; __device__ __forceinline__ unsigned cvt_pk_bf16(float lo, float hi) { return ::cvtpk(lo, hi); }
;     __device__ __forceinline__ void operator()(const f32x4 (&acc)[2][2][4][2], const Unit& u, int wr, int wc, int fr, int fq, int) const {
;     ...
;             for (int m = 0; m < 4; ++m) { const int row = row0 + ai * HALF + m * 16; const size_t off = (size_t)row * 2048 + col0; float s = 0.f;
; #pragma unroll
;                 for (int bj = 0; bj < 2; ++bj)
; #pragma unroll
;                     for (int n = 0; n < 2; ++n) { const size_t o2 = off + bj * HALF + n * 16; f32x4 bs;
;                         if (MODE == 0) bs = __builtin_nontemporal_load((const f32x4*)(base + o2));
;                         else { const u32x2 b2 = *(const u32x2*)(xb + o2); bs[0] = __builtin_bit_cast(float, b2.x << 16); bs[1] = __builtin_bit_cast(float, b2.x & 0xffff0000u); bs[2] = __builtin_bit_cast(float, b2.y << 16); bs[3] = __builtin_bit_cast(float, b2.y & 0xffff0000u); }
;                         const f32x4 o = bs + acc[ai][bj][m][n];
;                         if (MODE == 2) __builtin_nontemporal_store(o, (f32x4*)(out + o2));
;                         else { s += (o[0] * o[0] + o[1] * o[1]) + (o[2] * o[2] + o[3] * o[3]); u32x2 w; w.x = cvt_pk_bf16(o[0], o[1]); w.y = cvt_pk_bf16(o[2], o[3]); *(u32x2*)(xb + o2) = w; } }
;                 if (MODE != 2) { s += __shfl_xor(s, 16); s += __shfl_xor(s, 32); if (fq == 0) ssq[(size_t)row * 32 + u.pn * 4 + wc] = s; } }
.LBB0_590:
	s_or_b64 exec, exec, s[24:25]
	v_or_b32_e32 v112, 16, v144
	s_waitcnt lgkmcnt(0)
	v_ashrrev_i32_e32 v113, 31, v112
	v_lshlrev_b64 v[114:115], 11, v[112:113]
	v_readlane_b32 s48, v237, 29
	v_lshl_add_u64 v[118:119], v[114:115], 0, v[142:143]
	v_readlane_b32 s49, v237, 30
	v_readlane_b32 s50, v237, 31
	v_readlane_b32 s51, v237, 32
	v_lshl_add_u64 v[120:121], v[118:119], 2, s[48:49]
	s_waitcnt vmcnt(19)
	s_nop 1
	v_mov_b32_e32 v114, v188
	v_mov_b32_e32 v115, v189
	v_mov_b32_e32 v116, v190
	v_mov_b32_e32 v117, v191
	v_add_u32_e32 v171, 0x120000, v170
	global_load_dwordx4 v[188:191], v171, s[48:49] nt
	v_readlane_b32 s52, v237, 33
	v_readlane_b32 s53, v237, 34
	v_readlane_b32 s54, v237, 35
	v_readlane_b32 s55, v237, 36
	v_readlane_b32 s56, v237, 37
	v_readlane_b32 s57, v237, 38
	v_readlane_b32 s58, v237, 39
	v_readlane_b32 s59, v237, 40
	v_readlane_b32 s60, v237, 41
	v_readlane_b32 s61, v237, 42
	v_readlane_b32 s62, v237, 43
	v_readlane_b32 s63, v237, 44
	v_pk_add_f32 v[110:111], v[110:111], v[116:117]
	v_pk_add_f32 v[108:109], v[108:109], v[114:115]
	v_mul_f32_e32 v115, v111, v111
	v_mul_f32_e32 v114, v109, v109
	v_fmac_f32_e32 v114, v108, v108
	v_fmac_f32_e32 v115, v110, v110
	v_add_f32_e32 v116, v114, v115
	v_lshlrev_b64 v[114:115], 1, v[118:119]
	v_cvt_pk_bf16_f32 v108, v108, v109
	v_cvt_pk_bf16_f32 v109, v110, v111
	v_lshl_add_u64 v[110:111], s[80:81], 0, v[114:115]
	global_store_dwordx2 v[110:111], v[108:109], off
	s_waitcnt vmcnt(20)
	s_nop 1
	v_mov_b32_e32 v108, v192
	v_mov_b32_e32 v109, v193
	v_mov_b32_e32 v110, v194
	v_mov_b32_e32 v111, v195
	global_load_dwordx4 v[192:195], v171, s[48:49] offset:64 nt
	v_pk_add_f32 v[106:107], v[106:107], v[110:111]
	v_pk_add_f32 v[104:105], v[104:105], v[108:109]
	v_mul_f32_e32 v109, v107, v107
	v_mul_f32_e32 v108, v105, v105
	v_fmac_f32_e32 v108, v104, v104
	v_fmac_f32_e32 v109, v106, v106
	v_cvt_pk_bf16_f32 v104, v104, v105
	v_cvt_pk_bf16_f32 v105, v106, v107
	v_or_b32_e32 v106, 32, v114
	v_mov_b32_e32 v107, v115
	v_lshl_add_u64 v[106:107], s[80:81], 0, v[106:107]
	global_store_dwordx2 v[106:107], v[104:105], off
	s_waitcnt vmcnt(21)
	s_nop 1
	v_mov_b32_e32 v104, v196
	v_mov_b32_e32 v105, v197
	v_mov_b32_e32 v106, v198
	v_mov_b32_e32 v107, v199
	global_load_dwordx4 v[196:199], v171, s[48:49] offset:512 nt
	v_add_f32_e32 v108, v108, v109
	v_add_f32_e32 v108, v116, v108
	v_pk_add_f32 v[102:103], v[102:103], v[106:107]
	v_pk_add_f32 v[100:101], v[100:101], v[104:105]
	v_mul_f32_e32 v105, v103, v103
	v_mul_f32_e32 v104, v101, v101
	v_fmac_f32_e32 v104, v100, v100
	v_fmac_f32_e32 v105, v102, v102
	v_cvt_pk_bf16_f32 v100, v100, v101
	v_cvt_pk_bf16_f32 v101, v102, v103
	v_or_b32_e32 v102, 0x100, v114
	v_mov_b32_e32 v103, v115
	v_lshl_add_u64 v[102:103], s[80:81], 0, v[102:103]
	global_store_dwordx2 v[102:103], v[100:101], off
	s_waitcnt vmcnt(22)
	s_nop 1
	v_mov_b32_e32 v100, v200
	v_mov_b32_e32 v101, v201
	v_mov_b32_e32 v102, v202
	v_mov_b32_e32 v103, v203
	global_load_dwordx4 v[200:203], v171, s[48:49] offset:576 nt
	v_add_f32_e32 v104, v104, v105
	v_add_f32_e32 v104, v108, v104
	v_or_b32_e32 v114, 0x120, v114
	v_pk_add_f32 v[98:99], v[98:99], v[102:103]
	v_pk_add_f32 v[96:97], v[96:97], v[100:101]
	v_mul_f32_e32 v101, v99, v99
	v_mul_f32_e32 v100, v97, v97
	v_fmac_f32_e32 v100, v96, v96
	v_fmac_f32_e32 v101, v98, v98
	v_add_f32_e32 v100, v100, v101
	v_add_f32_e32 v100, v104, v100
	v_cvt_pk_bf16_f32 v96, v96, v97
	v_cvt_pk_bf16_f32 v97, v98, v99
	v_lshl_add_u64 v[98:99], s[80:81], 0, v[114:115]
	global_store_dwordx2 v[98:99], v[96:97], off
	ds_bpermute_b32 v96, v153, v100
	s_waitcnt lgkmcnt(0)
	v_add_f32_e32 v96, v100, v96
	ds_bpermute_b32 v97, v152, v96
	s_and_saveexec_b64 s[24:25], s[8:9]
	s_cbranch_execz .LBB0_592
	v_readlane_b32 s26, v237, 48
	v_lshlrev_b64 v[98:99], 7, v[112:113]
	v_readlane_b32 s27, v237, 49
	s_lshl_b32 s0, s40, 2
	s_waitcnt lgkmcnt(0)
	v_add_f32_e32 v96, v96, v97
	v_lshl_add_u64 v[98:99], s[26:27], 0, v[98:99]
	v_lshl_add_u64 v[98:99], s[22:23], 2, v[98:99]
	v_lshl_add_u64 v[98:99], v[98:99], 0, s[0:1]
	global_store_dword v[98:99], v96, off
.LBB0_592:
	s_or_b64 exec, exec, s[24:25]
	v_or_b32_e32 v96, 32, v144
	s_waitcnt lgkmcnt(0)
	v_ashrrev_i32_e32 v97, 31, v96
	v_lshlrev_b64 v[98:99], 11, v[96:97]
	v_readlane_b32 s48, v237, 29
	v_lshl_add_u64 v[102:103], v[98:99], 0, v[142:143]
	v_readlane_b32 s49, v237, 30
	v_readlane_b32 s50, v237, 31
	v_readlane_b32 s51, v237, 32
	v_lshl_add_u64 v[104:105], v[102:103], 2, s[48:49]
	s_waitcnt vmcnt(23)
	s_nop 1
	v_mov_b32_e32 v98, v204
	v_mov_b32_e32 v99, v205
	v_mov_b32_e32 v100, v206
	v_mov_b32_e32 v101, v207
	v_add_u32_e32 v171, 0x140000, v170
	global_load_dwordx4 v[204:207], v171, s[48:49] nt
	v_readlane_b32 s52, v237, 33
	v_readlane_b32 s53, v237, 34
	v_readlane_b32 s54, v237, 35
	v_readlane_b32 s55, v237, 36
	v_readlane_b32 s56, v237, 37
	v_readlane_b32 s57, v237, 38
	v_readlane_b32 s58, v237, 39
	v_readlane_b32 s59, v237, 40
	v_readlane_b32 s60, v237, 41
	v_readlane_b32 s61, v237, 42
	v_readlane_b32 s62, v237, 43
	v_readlane_b32 s63, v237, 44
	v_pk_add_f32 v[94:95], v[94:95], v[100:101]
	v_pk_add_f32 v[92:93], v[92:93], v[98:99]
	v_mul_f32_e32 v99, v95, v95
	v_mul_f32_e32 v98, v93, v93
	v_fmac_f32_e32 v98, v92, v92
	v_fmac_f32_e32 v99, v94, v94
	v_add_f32_e32 v100, v98, v99
	v_lshlrev_b64 v[98:99], 1, v[102:103]
	v_cvt_pk_bf16_f32 v92, v92, v93
	v_cvt_pk_bf16_f32 v93, v94, v95
	v_lshl_add_u64 v[94:95], s[80:81], 0, v[98:99]
	global_store_dwordx2 v[94:95], v[92:93], off
	s_waitcnt vmcnt(24)
; __device__ __forceinline__ unsigned cvt_pk_bf16(float lo, float hi) { return ::cvtpk(lo, hi); }
;     __device__ __forceinline__ void operator()(const f32x4 (&acc)[2][2][4][2], const Unit& u, int wr, int wc, int fr, int fq, int) const {
;     ...
;             for (int m = 0; m < 4; ++m) { const int row = row0 + ai * HALF + m * 16; const size_t off = (size_t)row * 2048 + col0; float s = 0.f;
; #pragma unroll
;                 for (int bj = 0; bj < 2; ++bj)
; #pragma unroll
;                     for (int n = 0; n < 2; ++n) { const size_t o2 = off + bj * HALF + n * 16; f32x4 bs;
;                         if (MODE == 0) bs = __builtin_nontemporal_load((const f32x4*)(base + o2));
;                         else { const u32x2 b2 = *(const u32x2*)(xb + o2); bs[0] = __builtin_bit_cast(float, b2.x << 16); bs[1] = __builtin_bit_cast(float, b2.x & 0xffff0000u); bs[2] = __builtin_bit_cast(float, b2.y << 16); bs[3] = __builtin_bit_cast(float, b2.y & 0xffff0000u); }
;                         const f32x4 o = bs + acc[ai][bj][m][n];
;                         if (MODE == 2) __builtin_nontemporal_store(o, (f32x4*)(out + o2));
;                         else { s += (o[0] * o[0] + o[1] * o[1]) + (o[2] * o[2] + o[3] * o[3]); u32x2 w; w.x = cvt_pk_bf16(o[0], o[1]); w.y = cvt_pk_bf16(o[2], o[3]); *(u32x2*)(xb + o2) = w; } }
;                 if (MODE != 2) { s += __shfl_xor(s, 16); s += __shfl_xor(s, 32); if (fq == 0) ssq[(size_t)row * 32 + u.pn * 4 + wc] = s; } }
	s_nop 1
	v_mov_b32_e32 v92, v208
	v_mov_b32_e32 v93, v209
	v_mov_b32_e32 v94, v210
	v_mov_b32_e32 v95, v211
	global_load_dwordx4 v[208:211], v171, s[48:49] offset:64 nt
	v_pk_add_f32 v[90:91], v[90:91], v[94:95]
	v_pk_add_f32 v[88:89], v[88:89], v[92:93]
	v_mul_f32_e32 v93, v91, v91
	v_mul_f32_e32 v92, v89, v89
	v_fmac_f32_e32 v92, v88, v88
	v_fmac_f32_e32 v93, v90, v90
	v_cvt_pk_bf16_f32 v88, v88, v89
	v_cvt_pk_bf16_f32 v89, v90, v91
	v_or_b32_e32 v90, 32, v98
	v_mov_b32_e32 v91, v99
	v_lshl_add_u64 v[90:91], s[80:81], 0, v[90:91]
	global_store_dwordx2 v[90:91], v[88:89], off
	s_waitcnt vmcnt(25)
	s_nop 1
	v_mov_b32_e32 v88, v212
	v_mov_b32_e32 v89, v213
	v_mov_b32_e32 v90, v214
	v_mov_b32_e32 v91, v215
	global_load_dwordx4 v[212:215], v171, s[48:49] offset:512 nt
	v_add_f32_e32 v92, v92, v93
	v_add_f32_e32 v92, v100, v92
	v_pk_add_f32 v[86:87], v[86:87], v[90:91]
	v_pk_add_f32 v[84:85], v[84:85], v[88:89]
	v_mul_f32_e32 v89, v87, v87
	v_mul_f32_e32 v88, v85, v85
	v_fmac_f32_e32 v88, v84, v84
	v_fmac_f32_e32 v89, v86, v86
	v_cvt_pk_bf16_f32 v84, v84, v85
	v_cvt_pk_bf16_f32 v85, v86, v87
	v_or_b32_e32 v86, 0x100, v98
	v_mov_b32_e32 v87, v99
	v_lshl_add_u64 v[86:87], s[80:81], 0, v[86:87]
	global_store_dwordx2 v[86:87], v[84:85], off
	s_waitcnt vmcnt(26)
	s_nop 1
	v_mov_b32_e32 v84, v216
	v_mov_b32_e32 v85, v217
	v_mov_b32_e32 v86, v218
	v_mov_b32_e32 v87, v219
	global_load_dwordx4 v[216:219], v171, s[48:49] offset:576 nt
	v_add_f32_e32 v88, v88, v89
	v_add_f32_e32 v88, v92, v88
	v_or_b32_e32 v98, 0x120, v98
	v_pk_add_f32 v[82:83], v[82:83], v[86:87]
	v_pk_add_f32 v[80:81], v[80:81], v[84:85]
	v_mul_f32_e32 v85, v83, v83
	v_mul_f32_e32 v84, v81, v81
	v_fmac_f32_e32 v84, v80, v80
	v_fmac_f32_e32 v85, v82, v82
	v_add_f32_e32 v84, v84, v85
	v_add_f32_e32 v84, v88, v84
	v_cvt_pk_bf16_f32 v80, v80, v81
	v_cvt_pk_bf16_f32 v81, v82, v83
	v_lshl_add_u64 v[82:83], s[80:81], 0, v[98:99]
	global_store_dwordx2 v[82:83], v[80:81], off
	ds_bpermute_b32 v80, v153, v84
	s_waitcnt lgkmcnt(0)
	v_add_f32_e32 v80, v84, v80
	ds_bpermute_b32 v81, v152, v80
	s_and_saveexec_b64 s[24:25], s[8:9]
	s_cbranch_execz .LBB0_594
	v_readlane_b32 s26, v237, 48
	v_lshlrev_b64 v[82:83], 7, v[96:97]
	v_readlane_b32 s27, v237, 49
	s_lshl_b32 s0, s40, 2
	s_waitcnt lgkmcnt(0)
	v_add_f32_e32 v80, v80, v81
	v_lshl_add_u64 v[82:83], s[26:27], 0, v[82:83]
	v_lshl_add_u64 v[82:83], s[22:23], 2, v[82:83]
	v_lshl_add_u64 v[82:83], v[82:83], 0, s[0:1]
	global_store_dword v[82:83], v80, off
.LBB0_594:
	s_or_b64 exec, exec, s[24:25]
	v_or_b32_e32 v80, 48, v144
	s_waitcnt lgkmcnt(0)
	v_ashrrev_i32_e32 v81, 31, v80
	v_lshlrev_b64 v[82:83], 11, v[80:81]
	v_readlane_b32 s48, v237, 29
	v_lshl_add_u64 v[86:87], v[82:83], 0, v[142:143]
	v_readlane_b32 s49, v237, 30
	v_readlane_b32 s50, v237, 31
	v_readlane_b32 s51, v237, 32
	v_lshl_add_u64 v[88:89], v[86:87], 2, s[48:49]
	s_waitcnt vmcnt(27)
	s_nop 1
	v_mov_b32_e32 v82, v220
	v_mov_b32_e32 v83, v221
	v_mov_b32_e32 v84, v222
	v_mov_b32_e32 v85, v223
	v_add_u32_e32 v171, 0x160000, v170
	global_load_dwordx4 v[220:223], v171, s[48:49] nt
	v_readlane_b32 s52, v237, 33
	v_readlane_b32 s53, v237, 34
	v_readlane_b32 s54, v237, 35
	v_readlane_b32 s55, v237, 36
	v_readlane_b32 s56, v237, 37
	v_readlane_b32 s57, v237, 38
	v_readlane_b32 s58, v237, 39
	v_readlane_b32 s59, v237, 40
	v_readlane_b32 s60, v237, 41
	v_readlane_b32 s61, v237, 42
	v_readlane_b32 s62, v237, 43
	v_readlane_b32 s63, v237, 44
	v_pk_add_f32 v[78:79], v[78:79], v[84:85]
	v_pk_add_f32 v[76:77], v[76:77], v[82:83]
	v_mul_f32_e32 v83, v79, v79
	v_mul_f32_e32 v82, v77, v77
	v_fmac_f32_e32 v82, v76, v76
	v_fmac_f32_e32 v83, v78, v78
	v_add_f32_e32 v84, v82, v83
	v_lshlrev_b64 v[82:83], 1, v[86:87]
	v_cvt_pk_bf16_f32 v76, v76, v77
	v_cvt_pk_bf16_f32 v77, v78, v79
	v_lshl_add_u64 v[78:79], s[80:81], 0, v[82:83]
	global_store_dwordx2 v[78:79], v[76:77], off
	s_waitcnt vmcnt(28)
	s_nop 1
	v_mov_b32_e32 v76, v224
	v_mov_b32_e32 v77, v225
	v_mov_b32_e32 v78, v226
	v_mov_b32_e32 v79, v227
	global_load_dwordx4 v[224:227], v171, s[48:49] offset:64 nt
	v_pk_add_f32 v[74:75], v[74:75], v[78:79]
	v_pk_add_f32 v[72:73], v[72:73], v[76:77]
	v_mul_f32_e32 v77, v75, v75
	v_mul_f32_e32 v76, v73, v73
	v_fmac_f32_e32 v76, v72, v72
	v_fmac_f32_e32 v77, v74, v74
	v_cvt_pk_bf16_f32 v72, v72, v73
	v_cvt_pk_bf16_f32 v73, v74, v75
	v_or_b32_e32 v74, 32, v82
	v_mov_b32_e32 v75, v83
	v_lshl_add_u64 v[74:75], s[80:81], 0, v[74:75]
	global_store_dwordx2 v[74:75], v[72:73], off
	s_waitcnt vmcnt(29)
	s_nop 1
	v_mov_b32_e32 v72, v228
	v_mov_b32_e32 v73, v229
	v_mov_b32_e32 v74, v230
	v_mov_b32_e32 v75, v231
	global_load_dwordx4 v[228:231], v171, s[48:49] offset:512 nt
	v_add_f32_e32 v76, v76, v77
	v_add_f32_e32 v76, v84, v76
	v_pk_add_f32 v[70:71], v[70:71], v[74:75]
	v_pk_add_f32 v[68:69], v[68:69], v[72:73]
	v_mul_f32_e32 v73, v71, v71
	v_mul_f32_e32 v72, v69, v69
	v_fmac_f32_e32 v72, v68, v68
	v_fmac_f32_e32 v73, v70, v70
	v_cvt_pk_bf16_f32 v68, v68, v69
	v_cvt_pk_bf16_f32 v69, v70, v71
	v_or_b32_e32 v70, 0x100, v82
	v_mov_b32_e32 v71, v83
	v_lshl_add_u64 v[70:71], s[80:81], 0, v[70:71]
	global_store_dwordx2 v[70:71], v[68:69], off
	s_waitcnt vmcnt(30)
	s_nop 1
	v_mov_b32_e32 v68, v232
	v_mov_b32_e32 v69, v233
	v_mov_b32_e32 v70, v234
	v_mov_b32_e32 v71, v235
	global_load_dwordx4 v[232:235], v171, s[48:49] offset:576 nt
	v_add_f32_e32 v72, v72, v73
	v_add_f32_e32 v72, v76, v72
	v_or_b32_e32 v82, 0x120, v82
	v_pk_add_f32 v[66:67], v[66:67], v[70:71]
	v_pk_add_f32 v[64:65], v[64:65], v[68:69]
	v_mul_f32_e32 v69, v67, v67
	v_mul_f32_e32 v68, v65, v65
	v_fmac_f32_e32 v68, v64, v64
	v_fmac_f32_e32 v69, v66, v66
	v_add_f32_e32 v68, v68, v69
	v_add_f32_e32 v68, v72, v68
	v_cvt_pk_bf16_f32 v64, v64, v65
	v_cvt_pk_bf16_f32 v65, v66, v67
	v_lshl_add_u64 v[66:67], s[80:81], 0, v[82:83]
	global_store_dwordx2 v[66:67], v[64:65], off
	ds_bpermute_b32 v64, v153, v68
	s_waitcnt lgkmcnt(0)
	v_add_f32_e32 v64, v68, v64
	ds_bpermute_b32 v65, v152, v64
	s_and_saveexec_b64 s[24:25], s[8:9]
	s_cbranch_execz .LBB0_596
	v_readlane_b32 s26, v237, 48
	v_lshlrev_b64 v[66:67], 7, v[80:81]
	v_readlane_b32 s27, v237, 49
	s_lshl_b32 s0, s40, 2
	s_waitcnt lgkmcnt(0)
	v_add_f32_e32 v64, v64, v65
	v_lshl_add_u64 v[66:67], s[26:27], 0, v[66:67]
	v_lshl_add_u64 v[66:67], s[22:23], 2, v[66:67]
	v_lshl_add_u64 v[66:67], v[66:67], 0, s[0:1]
	global_store_dword v[66:67], v64, off
; __device__ __forceinline__ unsigned cvt_pk_bf16(float lo, float hi) { return ::cvtpk(lo, hi); }
;     __device__ __forceinline__ void operator()(const f32x4 (&acc)[2][2][4][2], const Unit& u, int wr, int wc, int fr, int fq, int) const {
;     ...
;             for (int m = 0; m < 4; ++m) { const int row = row0 + ai * HALF + m * 16; const size_t off = (size_t)row * 2048 + col0; float s = 0.f;
; #pragma unroll
;                 for (int bj = 0; bj < 2; ++bj)
; #pragma unroll
;                     for (int n = 0; n < 2; ++n) { const size_t o2 = off + bj * HALF + n * 16; f32x4 bs;
;                         if (MODE == 0) bs = __builtin_nontemporal_load((const f32x4*)(base + o2));
;                         else { const u32x2 b2 = *(const u32x2*)(xb + o2); bs[0] = __builtin_bit_cast(float, b2.x << 16); bs[1] = __builtin_bit_cast(float, b2.x & 0xffff0000u); bs[2] = __builtin_bit_cast(float, b2.y << 16); bs[3] = __builtin_bit_cast(float, b2.y & 0xffff0000u); }
;                         const f32x4 o = bs + acc[ai][bj][m][n];
;                         if (MODE == 2) __builtin_nontemporal_store(o, (f32x4*)(out + o2));
;                         else { s += (o[0] * o[0] + o[1] * o[1]) + (o[2] * o[2] + o[3] * o[3]); u32x2 w; w.x = cvt_pk_bf16(o[0], o[1]); w.y = cvt_pk_bf16(o[2], o[3]); *(u32x2*)(xb + o2) = w; } }
;                 if (MODE != 2) { s += __shfl_xor(s, 16); s += __shfl_xor(s, 32); if (fq == 0) ssq[(size_t)row * 32 + u.pn * 4 + wc] = s; } }
.LBB0_596:
	s_or_b64 exec, exec, s[24:25]
	v_add_u32_e32 v64, 0x80, v144
	s_waitcnt lgkmcnt(0)
	v_ashrrev_i32_e32 v65, 31, v64
	v_lshlrev_b64 v[66:67], 11, v[64:65]
	v_readlane_b32 s48, v237, 29
	v_lshl_add_u64 v[70:71], v[66:67], 0, v[142:143]
	v_readlane_b32 s49, v237, 30
	v_readlane_b32 s50, v237, 31
	v_readlane_b32 s51, v237, 32
	v_lshl_add_u64 v[72:73], v[70:71], 2, s[48:49]
	s_waitcnt vmcnt(31)
	s_nop 1
	v_mov_b32_e32 v66, v162
	v_mov_b32_e32 v67, v163
	v_mov_b32_e32 v68, v164
	v_mov_b32_e32 v69, v165
	v_readlane_b32 s52, v237, 33
	v_readlane_b32 s53, v237, 34
	v_readlane_b32 s54, v237, 35
	v_readlane_b32 s55, v237, 36
	v_readlane_b32 s56, v237, 37
	v_readlane_b32 s57, v237, 38
	v_readlane_b32 s58, v237, 39
	v_readlane_b32 s59, v237, 40
	v_readlane_b32 s60, v237, 41
	v_readlane_b32 s61, v237, 42
	v_readlane_b32 s62, v237, 43
	v_readlane_b32 s63, v237, 44
	v_pk_add_f32 v[62:63], v[62:63], v[68:69]
	v_pk_add_f32 v[60:61], v[60:61], v[66:67]
	v_mul_f32_e32 v67, v63, v63
	v_mul_f32_e32 v66, v61, v61
	v_fmac_f32_e32 v66, v60, v60
	v_fmac_f32_e32 v67, v62, v62
	v_add_f32_e32 v68, v66, v67
	v_lshlrev_b64 v[66:67], 1, v[70:71]
	v_cvt_pk_bf16_f32 v60, v60, v61
	v_cvt_pk_bf16_f32 v61, v62, v63
	v_lshl_add_u64 v[62:63], s[80:81], 0, v[66:67]
	global_store_dwordx2 v[62:63], v[60:61], off
	s_waitcnt vmcnt(30)
	s_nop 1
	v_mov_b32_e32 v60, v166
	v_mov_b32_e32 v61, v167
	v_mov_b32_e32 v62, v168
	v_mov_b32_e32 v63, v169
	v_pk_add_f32 v[58:59], v[58:59], v[62:63]
	v_pk_add_f32 v[56:57], v[56:57], v[60:61]
	v_mul_f32_e32 v61, v59, v59
	v_mul_f32_e32 v60, v57, v57
	v_fmac_f32_e32 v60, v56, v56
	v_fmac_f32_e32 v61, v58, v58
	v_cvt_pk_bf16_f32 v56, v56, v57
	v_cvt_pk_bf16_f32 v57, v58, v59
	v_or_b32_e32 v58, 32, v66
	v_mov_b32_e32 v59, v67
	v_lshl_add_u64 v[58:59], s[80:81], 0, v[58:59]
	global_store_dwordx2 v[58:59], v[56:57], off
	s_waitcnt vmcnt(29)
	s_nop 1
	v_mov_b32_e32 v56, v180
	v_mov_b32_e32 v57, v181
	v_mov_b32_e32 v58, v182
	v_mov_b32_e32 v59, v183
	v_add_f32_e32 v60, v60, v61
	v_add_f32_e32 v60, v68, v60
	v_pk_add_f32 v[54:55], v[54:55], v[58:59]
	v_pk_add_f32 v[52:53], v[52:53], v[56:57]
	v_mul_f32_e32 v57, v55, v55
	v_mul_f32_e32 v56, v53, v53
	v_fmac_f32_e32 v56, v52, v52
	v_fmac_f32_e32 v57, v54, v54
	v_cvt_pk_bf16_f32 v52, v52, v53
	v_cvt_pk_bf16_f32 v53, v54, v55
	v_or_b32_e32 v54, 0x100, v66
	v_mov_b32_e32 v55, v67
	v_lshl_add_u64 v[54:55], s[80:81], 0, v[54:55]
	global_store_dwordx2 v[54:55], v[52:53], off
	s_waitcnt vmcnt(28)
	s_nop 1
	v_mov_b32_e32 v52, v184
	v_mov_b32_e32 v53, v185
	v_mov_b32_e32 v54, v186
	v_mov_b32_e32 v55, v187
	v_add_f32_e32 v56, v56, v57
	v_add_f32_e32 v56, v60, v56
	v_or_b32_e32 v66, 0x120, v66
	v_pk_add_f32 v[50:51], v[50:51], v[54:55]
	v_pk_add_f32 v[48:49], v[48:49], v[52:53]
	v_mul_f32_e32 v53, v51, v51
	v_mul_f32_e32 v52, v49, v49
	v_fmac_f32_e32 v52, v48, v48
	v_fmac_f32_e32 v53, v50, v50
	v_add_f32_e32 v52, v52, v53
	v_add_f32_e32 v52, v56, v52
	v_cvt_pk_bf16_f32 v48, v48, v49
	v_cvt_pk_bf16_f32 v49, v50, v51
	v_lshl_add_u64 v[50:51], s[80:81], 0, v[66:67]
	global_store_dwordx2 v[50:51], v[48:49], off
	ds_bpermute_b32 v48, v153, v52
	s_waitcnt lgkmcnt(0)
	v_add_f32_e32 v48, v52, v48
	ds_bpermute_b32 v49, v152, v48
	s_and_saveexec_b64 s[24:25], s[8:9]
	s_cbranch_execz .LBB0_598
	v_readlane_b32 s26, v237, 48
	v_lshlrev_b64 v[50:51], 7, v[64:65]
	v_readlane_b32 s27, v237, 49
	s_lshl_b32 s0, s40, 2
	s_waitcnt lgkmcnt(0)
	v_add_f32_e32 v48, v48, v49
	v_lshl_add_u64 v[50:51], s[26:27], 0, v[50:51]
	v_lshl_add_u64 v[50:51], s[22:23], 2, v[50:51]
	v_lshl_add_u64 v[50:51], v[50:51], 0, s[0:1]
	global_store_dword v[50:51], v48, off
.LBB0_598:
	s_or_b64 exec, exec, s[24:25]
	v_add_u32_e32 v48, 0x90, v144
	s_waitcnt lgkmcnt(0)
	v_ashrrev_i32_e32 v49, 31, v48
	v_lshlrev_b64 v[50:51], 11, v[48:49]
	v_readlane_b32 s48, v237, 29
	v_lshl_add_u64 v[54:55], v[50:51], 0, v[142:143]
	v_readlane_b32 s49, v237, 30
	v_readlane_b32 s50, v237, 31
	v_readlane_b32 s51, v237, 32
	v_lshl_add_u64 v[56:57], v[54:55], 2, s[48:49]
	s_waitcnt vmcnt(27)
	s_nop 1
	v_mov_b32_e32 v50, v188
	v_mov_b32_e32 v51, v189
	v_mov_b32_e32 v52, v190
	v_mov_b32_e32 v53, v191
	v_readlane_b32 s52, v237, 33
	v_readlane_b32 s53, v237, 34
	v_readlane_b32 s54, v237, 35
	v_readlane_b32 s55, v237, 36
	v_readlane_b32 s56, v237, 37
	v_readlane_b32 s57, v237, 38
	v_readlane_b32 s58, v237, 39
	v_readlane_b32 s59, v237, 40
	v_readlane_b32 s60, v237, 41
	v_readlane_b32 s61, v237, 42
	v_readlane_b32 s62, v237, 43
	v_readlane_b32 s63, v237, 44
	v_pk_add_f32 v[46:47], v[46:47], v[52:53]
	v_pk_add_f32 v[44:45], v[44:45], v[50:51]
	v_mul_f32_e32 v51, v47, v47
	v_mul_f32_e32 v50, v45, v45
	v_fmac_f32_e32 v50, v44, v44
	v_fmac_f32_e32 v51, v46, v46
	v_add_f32_e32 v52, v50, v51
	v_lshlrev_b64 v[50:51], 1, v[54:55]
	v_cvt_pk_bf16_f32 v44, v44, v45
	v_cvt_pk_bf16_f32 v45, v46, v47
	v_lshl_add_u64 v[46:47], s[80:81], 0, v[50:51]
	global_store_dwordx2 v[46:47], v[44:45], off
	s_waitcnt vmcnt(26)
	s_nop 1
	v_mov_b32_e32 v44, v192
	v_mov_b32_e32 v45, v193
	v_mov_b32_e32 v46, v194
	v_mov_b32_e32 v47, v195
	v_pk_add_f32 v[42:43], v[42:43], v[46:47]
	v_pk_add_f32 v[40:41], v[40:41], v[44:45]
	v_mul_f32_e32 v45, v43, v43
	v_mul_f32_e32 v44, v41, v41
	v_fmac_f32_e32 v44, v40, v40
	v_fmac_f32_e32 v45, v42, v42
	v_cvt_pk_bf16_f32 v40, v40, v41
	v_cvt_pk_bf16_f32 v41, v42, v43
	v_or_b32_e32 v42, 32, v50
	v_mov_b32_e32 v43, v51
	v_lshl_add_u64 v[42:43], s[80:81], 0, v[42:43]
	global_store_dwordx2 v[42:43], v[40:41], off
	s_waitcnt vmcnt(25)
	s_nop 1
	v_mov_b32_e32 v40, v196
	v_mov_b32_e32 v41, v197
	v_mov_b32_e32 v42, v198
	v_mov_b32_e32 v43, v199
	v_add_f32_e32 v44, v44, v45
	v_add_f32_e32 v44, v52, v44
	v_pk_add_f32 v[38:39], v[38:39], v[42:43]
	v_pk_add_f32 v[36:37], v[36:37], v[40:41]
	v_mul_f32_e32 v41, v39, v39
	v_mul_f32_e32 v40, v37, v37
	v_fmac_f32_e32 v40, v36, v36
	v_fmac_f32_e32 v41, v38, v38
	v_cvt_pk_bf16_f32 v36, v36, v37
	v_cvt_pk_bf16_f32 v37, v38, v39
	v_or_b32_e32 v38, 0x100, v50
	v_mov_b32_e32 v39, v51
	v_lshl_add_u64 v[38:39], s[80:81], 0, v[38:39]
	global_store_dwordx2 v[38:39], v[36:37], off
	s_waitcnt vmcnt(24)
	s_nop 1
	v_mov_b32_e32 v36, v200
	v_mov_b32_e32 v37, v201
	v_mov_b32_e32 v38, v202
	v_mov_b32_e32 v39, v203
	v_add_f32_e32 v40, v40, v41
	v_add_f32_e32 v40, v44, v40
	v_or_b32_e32 v50, 0x120, v50
	v_pk_add_f32 v[34:35], v[34:35], v[38:39]
	v_pk_add_f32 v[32:33], v[32:33], v[36:37]
	v_mul_f32_e32 v37, v35, v35
	v_mul_f32_e32 v36, v33, v33
	v_fmac_f32_e32 v36, v32, v32
	v_fmac_f32_e32 v37, v34, v34
	v_add_f32_e32 v36, v36, v37
	v_add_f32_e32 v36, v40, v36
	v_cvt_pk_bf16_f32 v32, v32, v33
	v_cvt_pk_bf16_f32 v33, v34, v35
	v_lshl_add_u64 v[34:35], s[80:81], 0, v[50:51]
	global_store_dwordx2 v[34:35], v[32:33], off
	ds_bpermute_b32 v32, v153, v36
	s_waitcnt lgkmcnt(0)
	v_add_f32_e32 v32, v36, v32
	ds_bpermute_b32 v33, v152, v32
	s_and_saveexec_b64 s[24:25], s[8:9]
	s_cbranch_execz .LBB0_600
; __device__ __forceinline__ unsigned cvt_pk_bf16(float lo, float hi) { return ::cvtpk(lo, hi); }
;     __device__ __forceinline__ void operator()(const f32x4 (&acc)[2][2][4][2], const Unit& u, int wr, int wc, int fr, int fq, int) const {
;     ...
;             for (int m = 0; m < 4; ++m) { const int row = row0 + ai * HALF + m * 16; const size_t off = (size_t)row * 2048 + col0; float s = 0.f;
; #pragma unroll
;                 for (int bj = 0; bj < 2; ++bj)
; #pragma unroll
;                     for (int n = 0; n < 2; ++n) { const size_t o2 = off + bj * HALF + n * 16; f32x4 bs;
;                         if (MODE == 0) bs = __builtin_nontemporal_load((const f32x4*)(base + o2));
;                         else { const u32x2 b2 = *(const u32x2*)(xb + o2); bs[0] = __builtin_bit_cast(float, b2.x << 16); bs[1] = __builtin_bit_cast(float, b2.x & 0xffff0000u); bs[2] = __builtin_bit_cast(float, b2.y << 16); bs[3] = __builtin_bit_cast(float, b2.y & 0xffff0000u); }
;                         const f32x4 o = bs + acc[ai][bj][m][n];
;                         if (MODE == 2) __builtin_nontemporal_store(o, (f32x4*)(out + o2));
;                         else { s += (o[0] * o[0] + o[1] * o[1]) + (o[2] * o[2] + o[3] * o[3]); u32x2 w; w.x = cvt_pk_bf16(o[0], o[1]); w.y = cvt_pk_bf16(o[2], o[3]); *(u32x2*)(xb + o2) = w; } }
;                 if (MODE != 2) { s += __shfl_xor(s, 16); s += __shfl_xor(s, 32); if (fq == 0) ssq[(size_t)row * 32 + u.pn * 4 + wc] = s; } }
	v_readlane_b32 s26, v237, 48
	v_lshlrev_b64 v[34:35], 7, v[48:49]
	v_readlane_b32 s27, v237, 49
	s_lshl_b32 s0, s40, 2
	s_waitcnt lgkmcnt(0)
	v_add_f32_e32 v32, v32, v33
	v_lshl_add_u64 v[34:35], s[26:27], 0, v[34:35]
	v_lshl_add_u64 v[34:35], s[22:23], 2, v[34:35]
	v_lshl_add_u64 v[34:35], v[34:35], 0, s[0:1]
	global_store_dword v[34:35], v32, off
.LBB0_600:
	s_or_b64 exec, exec, s[24:25]
	v_add_u32_e32 v32, 0xa0, v144
	s_waitcnt lgkmcnt(0)
	v_ashrrev_i32_e32 v33, 31, v32
	v_lshlrev_b64 v[34:35], 11, v[32:33]
	v_readlane_b32 s48, v237, 29
	v_lshl_add_u64 v[38:39], v[34:35], 0, v[142:143]
	v_readlane_b32 s49, v237, 30
	v_readlane_b32 s50, v237, 31
	v_readlane_b32 s51, v237, 32
	v_lshl_add_u64 v[40:41], v[38:39], 2, s[48:49]
	s_waitcnt vmcnt(23)
	s_nop 1
	v_mov_b32_e32 v34, v204
	v_mov_b32_e32 v35, v205
	v_mov_b32_e32 v36, v206
	v_mov_b32_e32 v37, v207
	v_readlane_b32 s52, v237, 33
	v_readlane_b32 s53, v237, 34
	v_readlane_b32 s54, v237, 35
	v_readlane_b32 s55, v237, 36
	v_readlane_b32 s56, v237, 37
	v_readlane_b32 s57, v237, 38
	v_readlane_b32 s58, v237, 39
	v_readlane_b32 s59, v237, 40
	v_readlane_b32 s60, v237, 41
	v_readlane_b32 s61, v237, 42
	v_readlane_b32 s62, v237, 43
	v_readlane_b32 s63, v237, 44
	v_pk_add_f32 v[30:31], v[30:31], v[36:37]
	v_pk_add_f32 v[28:29], v[28:29], v[34:35]
	v_mul_f32_e32 v35, v31, v31
	v_mul_f32_e32 v34, v29, v29
	v_fmac_f32_e32 v34, v28, v28
	v_fmac_f32_e32 v35, v30, v30
	v_add_f32_e32 v36, v34, v35
	v_lshlrev_b64 v[34:35], 1, v[38:39]
	v_cvt_pk_bf16_f32 v28, v28, v29
	v_cvt_pk_bf16_f32 v29, v30, v31
	v_lshl_add_u64 v[30:31], s[80:81], 0, v[34:35]
	global_store_dwordx2 v[30:31], v[28:29], off
	s_waitcnt vmcnt(22)
	s_nop 1
	v_mov_b32_e32 v28, v208
	v_mov_b32_e32 v29, v209
	v_mov_b32_e32 v30, v210
	v_mov_b32_e32 v31, v211
	v_pk_add_f32 v[26:27], v[26:27], v[30:31]
	v_pk_add_f32 v[24:25], v[24:25], v[28:29]
	v_mul_f32_e32 v29, v27, v27
	v_mul_f32_e32 v28, v25, v25
	v_fmac_f32_e32 v28, v24, v24
	v_fmac_f32_e32 v29, v26, v26
	v_cvt_pk_bf16_f32 v24, v24, v25
	v_cvt_pk_bf16_f32 v25, v26, v27
	v_or_b32_e32 v26, 32, v34
	v_mov_b32_e32 v27, v35
	v_lshl_add_u64 v[26:27], s[80:81], 0, v[26:27]
	global_store_dwordx2 v[26:27], v[24:25], off
	s_waitcnt vmcnt(21)
	s_nop 1
	v_mov_b32_e32 v24, v212
	v_mov_b32_e32 v25, v213
	v_mov_b32_e32 v26, v214
	v_mov_b32_e32 v27, v215
	v_add_f32_e32 v28, v28, v29
	v_add_f32_e32 v28, v36, v28
	v_pk_add_f32 v[22:23], v[22:23], v[26:27]
	v_pk_add_f32 v[20:21], v[20:21], v[24:25]
	v_mul_f32_e32 v25, v23, v23
	v_mul_f32_e32 v24, v21, v21
	v_fmac_f32_e32 v24, v20, v20
	v_fmac_f32_e32 v25, v22, v22
	v_cvt_pk_bf16_f32 v20, v20, v21
	v_cvt_pk_bf16_f32 v21, v22, v23
	v_or_b32_e32 v22, 0x100, v34
	v_mov_b32_e32 v23, v35
	v_lshl_add_u64 v[22:23], s[80:81], 0, v[22:23]
	global_store_dwordx2 v[22:23], v[20:21], off
	s_waitcnt vmcnt(20)
	s_nop 1
	v_mov_b32_e32 v20, v216
	v_mov_b32_e32 v21, v217
	v_mov_b32_e32 v22, v218
	v_mov_b32_e32 v23, v219
	v_add_f32_e32 v24, v24, v25
	v_add_f32_e32 v24, v28, v24
	v_or_b32_e32 v34, 0x120, v34
	v_pk_add_f32 v[18:19], v[18:19], v[22:23]
	v_pk_add_f32 v[16:17], v[16:17], v[20:21]
	v_mul_f32_e32 v21, v19, v19
	v_mul_f32_e32 v20, v17, v17
	v_fmac_f32_e32 v20, v16, v16
	v_fmac_f32_e32 v21, v18, v18
	v_add_f32_e32 v20, v20, v21
	v_add_f32_e32 v20, v24, v20
	v_cvt_pk_bf16_f32 v16, v16, v17
	v_cvt_pk_bf16_f32 v17, v18, v19
	v_lshl_add_u64 v[18:19], s[80:81], 0, v[34:35]
	global_store_dwordx2 v[18:19], v[16:17], off
	ds_bpermute_b32 v16, v153, v20
	s_waitcnt lgkmcnt(0)
	v_add_f32_e32 v16, v20, v16
	ds_bpermute_b32 v17, v152, v16
	s_and_saveexec_b64 s[24:25], s[8:9]
	s_cbranch_execz .LBB0_602
	v_readlane_b32 s26, v237, 48
	v_lshlrev_b64 v[18:19], 7, v[32:33]
	v_readlane_b32 s27, v237, 49
	s_lshl_b32 s0, s40, 2
	s_waitcnt lgkmcnt(0)
	v_add_f32_e32 v16, v16, v17
	v_lshl_add_u64 v[18:19], s[26:27], 0, v[18:19]
	v_lshl_add_u64 v[18:19], s[22:23], 2, v[18:19]
	v_lshl_add_u64 v[18:19], v[18:19], 0, s[0:1]
	global_store_dword v[18:19], v16, off
; __device__ __forceinline__ unsigned cvt_pk_bf16(float lo, float hi) { return ::cvtpk(lo, hi); }
;     __device__ __forceinline__ void operator()(const f32x4 (&acc)[2][2][4][2], const Unit& u, int wr, int wc, int fr, int fq, int) const {
;     ...
;             for (int m = 0; m < 4; ++m) { const int row = row0 + ai * HALF + m * 16; const size_t off = (size_t)row * 2048 + col0; float s = 0.f;
; #pragma unroll
;                 for (int bj = 0; bj < 2; ++bj)
; #pragma unroll
;                     for (int n = 0; n < 2; ++n) { const size_t o2 = off + bj * HALF + n * 16; f32x4 bs;
;                         if (MODE == 0) bs = __builtin_nontemporal_load((const f32x4*)(base + o2));
;                         else { const u32x2 b2 = *(const u32x2*)(xb + o2); bs[0] = __builtin_bit_cast(float, b2.x << 16); bs[1] = __builtin_bit_cast(float, b2.x & 0xffff0000u); bs[2] = __builtin_bit_cast(float, b2.y << 16); bs[3] = __builtin_bit_cast(float, b2.y & 0xffff0000u); }
;                         const f32x4 o = bs + acc[ai][bj][m][n];
;                         if (MODE == 2) __builtin_nontemporal_store(o, (f32x4*)(out + o2));
;                         else { s += (o[0] * o[0] + o[1] * o[1]) + (o[2] * o[2] + o[3] * o[3]); u32x2 w; w.x = cvt_pk_bf16(o[0], o[1]); w.y = cvt_pk_bf16(o[2], o[3]); *(u32x2*)(xb + o2) = w; } }
;                 if (MODE != 2) { s += __shfl_xor(s, 16); s += __shfl_xor(s, 32); if (fq == 0) ssq[(size_t)row * 32 + u.pn * 4 + wc] = s; } }
.LBB0_602:
	s_or_b64 exec, exec, s[24:25]
	v_add_u32_e32 v16, 0xb0, v144
	s_waitcnt lgkmcnt(0)
	v_ashrrev_i32_e32 v17, 31, v16
	v_lshlrev_b64 v[18:19], 11, v[16:17]
	v_readlane_b32 s48, v237, 29
	v_lshl_add_u64 v[22:23], v[18:19], 0, v[142:143]
	v_readlane_b32 s49, v237, 30
	v_readlane_b32 s50, v237, 31
	v_readlane_b32 s51, v237, 32
	v_lshl_add_u64 v[24:25], v[22:23], 2, s[48:49]
	s_waitcnt vmcnt(19)
	s_nop 1
	v_mov_b32_e32 v18, v220
	v_mov_b32_e32 v19, v221
	v_mov_b32_e32 v20, v222
	v_mov_b32_e32 v21, v223
	v_readlane_b32 s52, v237, 33
	v_readlane_b32 s53, v237, 34
	v_readlane_b32 s54, v237, 35
	v_readlane_b32 s55, v237, 36
	v_readlane_b32 s56, v237, 37
	v_readlane_b32 s57, v237, 38
	v_readlane_b32 s58, v237, 39
	v_readlane_b32 s59, v237, 40
	v_readlane_b32 s60, v237, 41
	v_readlane_b32 s61, v237, 42
	v_readlane_b32 s62, v237, 43
	v_readlane_b32 s63, v237, 44
	v_pk_add_f32 v[14:15], v[14:15], v[20:21]
	v_pk_add_f32 v[12:13], v[12:13], v[18:19]
	v_mul_f32_e32 v19, v15, v15
	v_mul_f32_e32 v18, v13, v13
	v_fmac_f32_e32 v18, v12, v12
	v_fmac_f32_e32 v19, v14, v14
	v_add_f32_e32 v20, v18, v19
	v_lshlrev_b64 v[18:19], 1, v[22:23]
	v_cvt_pk_bf16_f32 v12, v12, v13
	v_cvt_pk_bf16_f32 v13, v14, v15
	v_lshl_add_u64 v[14:15], s[80:81], 0, v[18:19]
	global_store_dwordx2 v[14:15], v[12:13], off
	s_waitcnt vmcnt(18)
	s_nop 1
	v_mov_b32_e32 v12, v224
	v_mov_b32_e32 v13, v225
	v_mov_b32_e32 v14, v226
	v_mov_b32_e32 v15, v227
	v_pk_add_f32 v[10:11], v[10:11], v[14:15]
	v_pk_add_f32 v[8:9], v[8:9], v[12:13]
	v_mul_f32_e32 v13, v11, v11
	v_mul_f32_e32 v12, v9, v9
	v_fmac_f32_e32 v12, v8, v8
	v_fmac_f32_e32 v13, v10, v10
	v_cvt_pk_bf16_f32 v8, v8, v9
	v_cvt_pk_bf16_f32 v9, v10, v11
	v_or_b32_e32 v10, 32, v18
	v_mov_b32_e32 v11, v19
	v_lshl_add_u64 v[10:11], s[80:81], 0, v[10:11]
	global_store_dwordx2 v[10:11], v[8:9], off
	s_waitcnt vmcnt(17)
	s_nop 1
	v_mov_b32_e32 v8, v228
	v_mov_b32_e32 v9, v229
	v_mov_b32_e32 v10, v230
	v_mov_b32_e32 v11, v231
	v_add_f32_e32 v12, v12, v13
	v_add_f32_e32 v12, v20, v12
	v_pk_add_f32 v[6:7], v[6:7], v[10:11]
	v_pk_add_f32 v[4:5], v[4:5], v[8:9]
	v_mul_f32_e32 v9, v7, v7
	v_mul_f32_e32 v8, v5, v5
	v_fmac_f32_e32 v8, v4, v4
	v_fmac_f32_e32 v9, v6, v6
	v_cvt_pk_bf16_f32 v4, v4, v5
	v_cvt_pk_bf16_f32 v5, v6, v7
	v_or_b32_e32 v6, 0x100, v18
	v_mov_b32_e32 v7, v19
	v_lshl_add_u64 v[6:7], s[80:81], 0, v[6:7]
	global_store_dwordx2 v[6:7], v[4:5], off
	s_waitcnt vmcnt(16)
	s_nop 1
	v_mov_b32_e32 v4, v232
	v_mov_b32_e32 v5, v233
	v_mov_b32_e32 v6, v234
	v_mov_b32_e32 v7, v235
	v_add_f32_e32 v8, v8, v9
	v_add_f32_e32 v8, v12, v8
	v_or_b32_e32 v18, 0x120, v18
	v_pk_add_f32 v[2:3], v[2:3], v[6:7]
	v_pk_add_f32 v[0:1], v[0:1], v[4:5]
	v_mul_f32_e32 v5, v3, v3
	v_mul_f32_e32 v4, v1, v1
	v_fmac_f32_e32 v4, v0, v0
	v_fmac_f32_e32 v5, v2, v2
	v_add_f32_e32 v4, v4, v5
	v_add_f32_e32 v4, v8, v4
	v_cvt_pk_bf16_f32 v0, v0, v1
	v_cvt_pk_bf16_f32 v1, v2, v3
	v_lshl_add_u64 v[2:3], s[80:81], 0, v[18:19]
	global_store_dwordx2 v[2:3], v[0:1], off
	ds_bpermute_b32 v0, v153, v4
	s_waitcnt lgkmcnt(0)
	v_add_f32_e32 v0, v4, v0
	ds_bpermute_b32 v1, v152, v0
	s_and_saveexec_b64 s[24:25], s[8:9]
	s_cbranch_execz .LBB0_604
	v_readlane_b32 s26, v237, 48
	v_lshlrev_b64 v[2:3], 7, v[16:17]
	v_readlane_b32 s27, v237, 49
	s_lshl_b32 s0, s40, 2
	s_waitcnt lgkmcnt(0)
	v_add_f32_e32 v0, v0, v1
	v_lshl_add_u64 v[2:3], s[26:27], 0, v[2:3]
	v_lshl_add_u64 v[2:3], s[22:23], 2, v[2:3]
	v_lshl_add_u64 v[2:3], v[2:3], 0, s[0:1]
	global_store_dword v[2:3], v0, off
